# attention phase: static priority raise for one of the two co-resident workgroups
# speedup vs baseline: 1.0075x; 1.0052x over previous
; DI bool softmax_bound_ok(const Params& p, int layer, int mode) {
;     ...
;   for (int i = lane; i < ng; i += 64) { aq = fmaxf(aq, fabsf(gq[i])); ak = fmaxf(ak, fabsf(gk[i])); }
;   if (mode == 2) { for (int i = lane; i < 256; i += 64) ab = fmaxf(ab, fabsf(p.rel_bias[i])); }
; #pragma unroll
;   for (int off = 1; off < 64; off <<= 1) { aq = fmaxf(aq, __shfl_xor(aq, off)); ak = fmaxf(ak, __shfl_xor(ak, off)); ab = fmaxf(ab, __shfl_xor(ab, off)); }
;   const float bound = ((mode == 1) ? 9.7979590f * aq * ak : 8.f * aq * ak + 2.f * ab) * LOG2E * 1.02f;
;   return __builtin_amdgcn_readfirstlane((bound < 100.f) ? 1 : 0) != 0;
; __global__ void __launch_bounds__(256, 2) hybrid_megakernel(Params p, int ph_lo, int ph_hi, int do_sync) {
;     ...
;         const bool fast1 = softmax_bound_ok(p, layer, 1), fast2 = softmax_bound_ok(p, layer, 2);
;         const bool xq = (s_xinfo[3] == 8);
;         int* ctr = (int*)(p.ws + WS_CTR) + (xq ? (16 + layer * 8 + t_cls) : layer);
;         const int limit = xq ? 384 : 3072;
;         while (true) {
;           if (tid == 0) s_item = atomicAdd(ctr, 1);
;           __syncthreads();
;           const int w = s_item;
;           __syncthreads();
;           if (w >= limit) break;
.LBB0_28:
	global_load_dword v11, v[0:1], off
	v_add_u32_e32 v10, 64, v10
	s_movk_i32 s5, 0xbf
	v_max_f32_e32 v2, v2, v2
	v_cmp_lt_u32_e32 vcc, s5, v10
	v_lshl_add_u64 v[0:1], v[0:1], 0, s[48:49]
	s_or_b64 s[6:7], vcc, s[6:7]
	s_waitcnt vmcnt(0)
	v_max_f32_e64 v11, |v11|, |v11|
	v_max_f32_e32 v2, v2, v11
	s_andn2_b64 exec, exec, s[6:7]
	s_cbranch_execnz .LBB0_28
	s_or_b64 exec, exec, s[6:7]
	s_waitcnt lgkmcnt(1)
	v_max_f32_e32 v0, v9, v9
	v_max_f32_e32 v1, v7, v7
	v_max_f32_e32 v0, v1, v0
	s_waitcnt lgkmcnt(0)
	v_max_f32_e32 v1, v8, v8
	v_max_f32_e32 v6, v6, v6
	v_max_f32_e32 v1, v6, v1
	v_mul_f32_e32 v0, 0x411cc471, v0
	v_mul_f32_e32 v0, v1, v0
	v_mul_f32_e32 v0, 0x3fb8aa3b, v0
	v_mul_f32_e32 v0, 0x3f828f5c, v0
	s_mov_b32 s10, 0x42c80000
	v_cmp_gt_f32_e32 vcc, s10, v0
	v_max_f32_e64 v4, |v4|, |v4|
	v_max_f32_e32 v4, 0, v4
	v_cndmask_b32_e64 v0, 0, 1, vcc
	ds_bpermute_b32 v6, v180, v2
	v_readfirstlane_b32 s5, v0
	v_max_f32_e64 v0, |v5|, |v5|
	v_max_f32_e32 v0, 0, v0
	ds_bpermute_b32 v1, v180, v0
	ds_bpermute_b32 v5, v180, v4
	v_max_f32_e32 v2, v2, v2
	s_bitcmp1_b32 s5, 0
	s_cselect_b64 s[6:7], -1, 0
	s_waitcnt lgkmcnt(1)
	v_max_f32_e32 v1, v1, v1
	v_max_f32_e32 v0, v0, v1
	s_waitcnt lgkmcnt(0)
	v_max_f32_e32 v1, v5, v5
	v_max_f32_e32 v1, v4, v1
	ds_bpermute_b32 v4, v181, v0
	v_max_f32_e32 v5, v6, v6
	ds_bpermute_b32 v6, v181, v1
	v_max_f32_e32 v2, v2, v5
	ds_bpermute_b32 v5, v181, v2
	s_waitcnt lgkmcnt(2)
	v_max_f32_e32 v4, v4, v4
	v_max_f32_e32 v0, v0, v4
	s_waitcnt lgkmcnt(1)
	v_max_f32_e32 v4, v6, v6
	ds_bpermute_b32 v6, v182, v0
	v_max_f32_e32 v1, v1, v4
	s_waitcnt lgkmcnt(1)
	v_max_f32_e32 v4, v5, v5
	ds_bpermute_b32 v5, v182, v1
	v_max_f32_e32 v2, v2, v4
	s_waitcnt lgkmcnt(1)
	v_max_f32_e32 v4, v6, v6
	ds_bpermute_b32 v6, v182, v2
	v_max_f32_e32 v0, v0, v4
	s_waitcnt lgkmcnt(1)
	v_max_f32_e32 v4, v5, v5
	ds_bpermute_b32 v5, v183, v0
	v_max_f32_e32 v1, v1, v4
	s_waitcnt lgkmcnt(1)
	v_max_f32_e32 v4, v6, v6
	ds_bpermute_b32 v6, v183, v1
	v_max_f32_e32 v2, v2, v4
	s_waitcnt lgkmcnt(1)
	v_max_f32_e32 v4, v5, v5
	ds_bpermute_b32 v5, v183, v2
	v_max_f32_e32 v0, v0, v4
	s_waitcnt lgkmcnt(1)
	v_max_f32_e32 v4, v6, v6
	ds_bpermute_b32 v6, v184, v0
	v_max_f32_e32 v1, v1, v4
	s_waitcnt lgkmcnt(1)
	v_max_f32_e32 v4, v5, v5
	ds_bpermute_b32 v5, v184, v1
	v_max_f32_e32 v2, v2, v4
	s_waitcnt lgkmcnt(1)
	v_max_f32_e32 v4, v6, v6
	ds_bpermute_b32 v6, v184, v2
	v_max_f32_e32 v0, v0, v4
	s_waitcnt lgkmcnt(1)
	v_max_f32_e32 v4, v5, v5
	v_max_f32_e32 v1, v1, v4
	ds_bpermute_b32 v4, v185, v0
	s_waitcnt lgkmcnt(1)
	v_max_f32_e32 v5, v6, v6
	ds_bpermute_b32 v6, v185, v1
	v_max_f32_e32 v2, v2, v5
	ds_bpermute_b32 v5, v185, v2
	s_xor_b64 s[6:7], s[6:7], -1
	s_waitcnt lgkmcnt(2)
	v_max_f32_e32 v4, v4, v4
	v_writelane_b32 v255, s6, 4
	v_max_f32_e32 v0, v0, v4
	s_waitcnt lgkmcnt(1)
	v_max_f32_e32 v4, v6, v6
	v_writelane_b32 v255, s7, 5
	v_max_f32_e32 v4, v1, v4
	s_waitcnt lgkmcnt(0)
	v_max_f32_e32 v1, v5, v5
	s_mov_b32 s6, 0x41000000
	v_max_f32_e32 v1, v2, v1
	s_mov_b32 s7, 2.0
	v_pk_mul_f32 v[0:1], v[0:1], s[6:7]
	v_readlane_b32 s12, v252, 46
	v_fmac_f32_e32 v1, v4, v0
	v_mul_f32_e32 v0, 0x3fb8aa3b, v1
	v_mul_f32_e32 v0, 0x3f828f5c, v0
	v_cmp_gt_f32_e32 vcc, s10, v0
	ds_read_b32 v1, v229
	v_readlane_b32 s10, v252, 6
	v_cndmask_b32_e64 v0, 0, 1, vcc
	v_readlane_b32 s13, v252, 47
	v_readfirstlane_b32 s5, v0
	s_bitcmp1_b32 s5, 0
	s_cselect_b64 s[6:7], -1, 0
	s_xor_b64 s[6:7], s[6:7], -1
	v_writelane_b32 v255, s6, 8
	s_waitcnt lgkmcnt(0)
	v_cmp_ne_u32_e64 s[44:45], 8, v1
	v_cmp_eq_u32_e64 s[46:47], 0, v213
	v_writelane_b32 v255, s7, 9
	v_readlane_b32 s7, v254, 35
	s_lshl_b32 s5, s7, 3
	s_add_i32 s5, s5, s10
	s_add_i32 s5, s5, 16
	v_readfirstlane_b32 s6, v1
	s_cmp_eq_u32 s6, 8
	s_movk_i32 s6, 0x180
	s_cselect_b32 s31, s6, 0xc00
	s_cselect_b32 s6, s5, s7
	s_ashr_i32 s7, s6, 31
	s_lshl_b64 s[6:7], s[6:7], 2
	s_add_u32 s18, s12, s6
	s_addc_u32 s19, s13, s7
	s_lshl_b32 s5, s10, 2
	s_ashr_i32 s6, s10, 1
	v_writelane_b32 v255, s6, 1
	s_and_b32 s5, s5, 4
	v_writelane_b32 v255, s5, 2
	s_and_b32 s5, s10, 1
	v_writelane_b32 v255, s5, 3
	s_getreg_b32 vcc_lo, hwreg(HW_REG_LDS_ALLOC, 0, 8)
	s_cmp_eq_u32 vcc_lo, 0
	s_cbranch_scc1 .Lattn_noprio
	s_setprio 1
.Lattn_noprio:
	s_branch .LBB0_33
.LBB0_30:
	s_lshl_b32 s16, s7, 7
	v_readlane_b32 s6, v252, 8
	v_lshl_add_u32 v2, s58, 12, v86
	v_mov_b64_e32 v[0:1], s[94:95]
	v_readlane_b32 s7, v252, 9
	v_mad_i64_i32 v[0:1], s[10:11], v2, s54, v[0:1]
	s_nop 0
	v_mov_b64_e32 v[36:37], s[6:7]
	v_lshl_add_u64 v[0:1], v[0:1], 0, s[16:17]
	v_mad_i64_i32 v[36:37], s[6:7], v2, s9, v[36:37]
	v_lshlrev_b32_e32 v2, 1, v91
	v_lshl_add_u64 v[0:1], v[0:1], 0, v[2:3]
	s_mov_b64 s[6:7], 0x4e98a80
	s_mov_b32 s5, 0x4e98000
	v_lshl_add_u64 v[38:39], v[36:37], 0, s[16:17]
	v_lshl_add_u64 v[36:37], v[0:1], 0, s[6:7]
	v_add_co_u32_e32 v0, vcc, s5, v0
	s_mov_b64 s[6:7], 0x70
	s_nop 0
	v_addc_co_u32_e32 v1, vcc, 0, v1, vcc
	global_load_dwordx2 v[0:1], v[0:1], off offset:2688
	s_waitcnt vmcnt(0)
	v_lshlrev_b32_e32 v40, 16, v0
	v_and_b32_e32 v41, 0xffff0000, v0
	v_mul_f32_e32 v42, 0xbfb8aa3b, v40
	v_mul_f32_e32 v43, 0xbfb8aa3b, v41
	v_exp_f32_e32 v42, v42
	v_exp_f32_e32 v43, v43
	v_lshlrev_b32_e32 v0, 16, v1
	v_and_b32_e32 v1, 0xffff0000, v1
	v_add_f32_e32 v42, 1.0, v42
	v_add_f32_e32 v43, 1.0, v43
	v_rcp_f32_e32 v42, v42
	v_rcp_f32_e32 v43, v43
	s_nop 0
	v_pk_mul_f32 v[40:41], v[42:43], v[40:41]
	s_nop 0
	v_pk_mul_f32 v[20:21], v[20:21], v[40:41]
	v_mul_f32_e32 v40, 0xbfb8aa3b, v0
	v_mul_f32_e32 v41, 0xbfb8aa3b, v1
	v_exp_f32_e32 v40, v40
	v_exp_f32_e32 v41, v41
	v_cvt_pk_bf16_f32 v20, v20, v21
	v_add_f32_e32 v40, 1.0, v40
	v_add_f32_e32 v41, 1.0, v41
	v_rcp_f32_e32 v40, v40
	v_rcp_f32_e32 v41, v41
	s_nop 0
	v_pk_mul_f32 v[0:1], v[40:41], v[0:1]
	s_nop 0
	v_pk_mul_f32 v[0:1], v[22:23], v[0:1]
	s_nop 0
	v_cvt_pk_bf16_f32 v21, v0, v1
	v_lshl_add_u64 v[0:1], v[38:39], 0, v[2:3]
	global_store_dwordx2 v[0:1], v[20:21], off
	global_load_dwordx2 v[20:21], v[36:37], off offset:16
	s_waitcnt vmcnt(0)
; DI uint32_t pack2(float a, float b) { f2_t v = {a, b}; bf2_t r = __builtin_convertvector(v, bf2_t); return __builtin_bit_cast(uint32_t, r); }
; DI float bflo(uint32_t u) { return __uint_as_float(u << 16); }
; DI float bfhi(uint32_t u) { return __uint_as_float(u & 0xffff0000u); }
; DI float fsigmoid(float x) { return frcp(1.f + fexp2(-LOG2E * x)); }
; template <int MODE, bool FAST>
; DI void attn_item(const Params& p, int layer, int b, int hd, int qt, char* smem) {
;     ...
;   const size_t tok = (size_t)(tokbase + tq);
;   const u16* zrow = PROJ + tok * LDP + O_ZA + MODE * 512 + hdl * 64;
;   u16* yrow = YBR + tok * LDY + MODE * 512 + hdl * 64;
; #pragma unroll
;   for (int dt = 0; dt < 2; ++dt)
; #pragma unroll
;     for (int g = 0; g < 4; ++g) {
;       const int d4 = dt * 32 + 8 * g + 4 * h;
;       uint2 zu = *(const uint2*)(zrow + d4);
;       float z0 = bflo(zu.x), z1 = bfhi(zu.x), z2 = bflo(zu.y), z3 = bfhi(zu.y);
;       float y0 = o[dt][4 * g] * inv, y1 = o[dt][4 * g + 1] * inv, y2 = o[dt][4 * g + 2] * inv, y3 = o[dt][4 * g + 3] * inv;
;       y0 *= z0 * fsigmoid(z0); y1 *= z1 * fsigmoid(z1); y2 *= z2 * fsigmoid(z2); y3 *= z3 * fsigmoid(z3);
;       *(uint2*)(yrow + d4) = make_uint2(pack2(y0, y1), pack2(y2, y3));
;     }
	v_lshlrev_b32_e32 v22, 16, v20
	v_mul_f32_e32 v2, 0xbfb8aa3b, v22
	v_exp_f32_e32 v2, v2
	v_and_b32_e32 v23, 0xffff0000, v20
	v_lshlrev_b32_e32 v20, 16, v21
	v_and_b32_e32 v21, 0xffff0000, v21
	v_add_f32_e32 v2, 1.0, v2
	v_rcp_f32_e32 v38, v2
	v_mul_f32_e32 v2, 0xbfb8aa3b, v23
	v_exp_f32_e32 v2, v2
	s_nop 0
	v_add_f32_e32 v2, 1.0, v2
	v_rcp_f32_e32 v39, v2
	v_mul_f32_e32 v2, 0xbfb8aa3b, v20
	v_exp_f32_e32 v2, v2
	v_pk_mul_f32 v[22:23], v[38:39], v[22:23]
	s_nop 0
	v_pk_mul_f32 v[22:23], v[24:25], v[22:23]
	v_add_f32_e32 v2, 1.0, v2
	v_rcp_f32_e32 v24, v2
	v_mul_f32_e32 v2, 0xbfb8aa3b, v21
	v_exp_f32_e32 v2, v2
	v_cvt_pk_bf16_f32 v22, v22, v23
	v_add_f32_e32 v2, 1.0, v2
	v_rcp_f32_e32 v25, v2
	s_nop 0
	v_pk_mul_f32 v[20:21], v[24:25], v[20:21]
	s_nop 0
	v_pk_mul_f32 v[20:21], v[26:27], v[20:21]
	s_nop 0
	v_cvt_pk_bf16_f32 v23, v20, v21
	global_load_dwordx2 v[20:21], v[36:37], off offset:32
	s_nop 0
	global_store_dwordx2 v[0:1], v[22:23], off offset:16
	s_waitcnt vmcnt(1)
	v_lshlrev_b32_e32 v22, 16, v20
	v_mul_f32_e32 v2, 0xbfb8aa3b, v22
	v_exp_f32_e32 v2, v2
	v_and_b32_e32 v23, 0xffff0000, v20
	v_lshlrev_b32_e32 v20, 16, v21
	v_and_b32_e32 v21, 0xffff0000, v21
	v_add_f32_e32 v2, 1.0, v2
	v_rcp_f32_e32 v24, v2
	v_mul_f32_e32 v2, 0xbfb8aa3b, v23
	v_exp_f32_e32 v2, v2
	s_nop 0
	v_add_f32_e32 v2, 1.0, v2
	v_rcp_f32_e32 v25, v2
	v_mul_f32_e32 v2, 0xbfb8aa3b, v20
	v_exp_f32_e32 v2, v2
	v_pk_mul_f32 v[22:23], v[24:25], v[22:23]
	s_nop 0
	v_pk_mul_f32 v[22:23], v[28:29], v[22:23]
	v_add_f32_e32 v2, 1.0, v2
	v_rcp_f32_e32 v24, v2
	v_mul_f32_e32 v2, 0xbfb8aa3b, v21
	v_exp_f32_e32 v2, v2
	v_cvt_pk_bf16_f32 v22, v22, v23
	v_add_f32_e32 v2, 1.0, v2
	v_rcp_f32_e32 v25, v2
	s_nop 0
	v_pk_mul_f32 v[20:21], v[24:25], v[20:21]
	s_nop 0
	v_pk_mul_f32 v[20:21], v[30:31], v[20:21]
	s_nop 0
	v_cvt_pk_bf16_f32 v23, v20, v21
	global_load_dwordx2 v[20:21], v[36:37], off offset:48
	s_nop 0
	global_store_dwordx2 v[0:1], v[22:23], off offset:32
	s_waitcnt vmcnt(1)
	v_lshlrev_b32_e32 v22, 16, v20
	v_mul_f32_e32 v2, 0xbfb8aa3b, v22
	v_exp_f32_e32 v2, v2
	v_and_b32_e32 v23, 0xffff0000, v20
	v_lshlrev_b32_e32 v20, 16, v21
	v_and_b32_e32 v21, 0xffff0000, v21
	v_add_f32_e32 v2, 1.0, v2
	v_rcp_f32_e32 v24, v2
	v_mul_f32_e32 v2, 0xbfb8aa3b, v23
	v_exp_f32_e32 v2, v2
	s_nop 0
	v_add_f32_e32 v2, 1.0, v2
	v_rcp_f32_e32 v25, v2
	v_mul_f32_e32 v2, 0xbfb8aa3b, v20
	v_exp_f32_e32 v2, v2
	v_pk_mul_f32 v[22:23], v[24:25], v[22:23]
	s_nop 0
	v_pk_mul_f32 v[22:23], v[32:33], v[22:23]
	v_add_f32_e32 v2, 1.0, v2
	v_rcp_f32_e32 v24, v2
	v_mul_f32_e32 v2, 0xbfb8aa3b, v21
	v_exp_f32_e32 v2, v2
	v_cvt_pk_bf16_f32 v22, v22, v23
	v_add_f32_e32 v2, 1.0, v2
	v_rcp_f32_e32 v25, v2
	s_nop 0
	v_pk_mul_f32 v[20:21], v[24:25], v[20:21]
	s_nop 0
	v_pk_mul_f32 v[20:21], v[34:35], v[20:21]
	s_nop 0
	v_cvt_pk_bf16_f32 v23, v20, v21
	global_load_dwordx2 v[20:21], v[36:37], off offset:64
	s_nop 0
	global_store_dwordx2 v[0:1], v[22:23], off offset:48
	s_waitcnt vmcnt(1)
	v_lshlrev_b32_e32 v22, 16, v20
	v_mul_f32_e32 v2, 0xbfb8aa3b, v22
	v_exp_f32_e32 v2, v2
	v_and_b32_e32 v23, 0xffff0000, v20
	v_lshlrev_b32_e32 v20, 16, v21
	v_and_b32_e32 v21, 0xffff0000, v21
	v_add_f32_e32 v2, 1.0, v2
	v_rcp_f32_e32 v24, v2
	v_mul_f32_e32 v2, 0xbfb8aa3b, v23
	v_exp_f32_e32 v2, v2
	s_nop 0
	v_add_f32_e32 v2, 1.0, v2
	v_rcp_f32_e32 v25, v2
	v_mul_f32_e32 v2, 0xbfb8aa3b, v20
	v_exp_f32_e32 v2, v2
	v_pk_mul_f32 v[22:23], v[24:25], v[22:23]
	s_nop 0
	v_pk_mul_f32 v[4:5], v[4:5], v[22:23]
	v_add_f32_e32 v2, 1.0, v2
	v_rcp_f32_e32 v22, v2
	v_mul_f32_e32 v2, 0xbfb8aa3b, v21
	v_exp_f32_e32 v2, v2
	v_cvt_pk_bf16_f32 v4, v4, v5
	v_add_f32_e32 v2, 1.0, v2
	v_rcp_f32_e32 v23, v2
	s_nop 0
	v_pk_mul_f32 v[20:21], v[22:23], v[20:21]
	s_nop 0
	v_pk_mul_f32 v[6:7], v[6:7], v[20:21]
	s_nop 0
	v_cvt_pk_bf16_f32 v5, v6, v7
	global_store_dwordx2 v[0:1], v[4:5], off offset:64
	global_load_dwordx2 v[4:5], v[36:37], off offset:80
	s_waitcnt vmcnt(0)
	v_lshlrev_b32_e32 v6, 16, v4
	v_mul_f32_e32 v2, 0xbfb8aa3b, v6
	v_exp_f32_e32 v2, v2
	v_and_b32_e32 v7, 0xffff0000, v4
	v_lshlrev_b32_e32 v4, 16, v5
	v_and_b32_e32 v5, 0xffff0000, v5
	v_add_f32_e32 v2, 1.0, v2
	v_rcp_f32_e32 v20, v2
	v_mul_f32_e32 v2, 0xbfb8aa3b, v7
	v_exp_f32_e32 v2, v2
	s_nop 0
	v_add_f32_e32 v2, 1.0, v2
	v_rcp_f32_e32 v21, v2
	v_mul_f32_e32 v2, 0xbfb8aa3b, v4
	v_exp_f32_e32 v2, v2
	v_pk_mul_f32 v[6:7], v[20:21], v[6:7]
	s_nop 0
	v_pk_mul_f32 v[6:7], v[8:9], v[6:7]
	v_add_f32_e32 v2, 1.0, v2
	v_rcp_f32_e32 v8, v2
	v_mul_f32_e32 v2, 0xbfb8aa3b, v5
	v_exp_f32_e32 v2, v2
	v_cvt_pk_bf16_f32 v6, v6, v7
	v_add_f32_e32 v2, 1.0, v2
	v_rcp_f32_e32 v9, v2
	s_nop 0
	v_pk_mul_f32 v[4:5], v[8:9], v[4:5]
	s_nop 0
	v_pk_mul_f32 v[4:5], v[10:11], v[4:5]
	s_nop 0
	v_cvt_pk_bf16_f32 v7, v4, v5
	global_load_dwordx2 v[4:5], v[36:37], off offset:96
	s_nop 0
	global_store_dwordx2 v[0:1], v[6:7], off offset:80
	s_waitcnt vmcnt(1)
	v_lshlrev_b32_e32 v6, 16, v4
	v_mul_f32_e32 v2, 0xbfb8aa3b, v6
	v_exp_f32_e32 v2, v2
	v_and_b32_e32 v7, 0xffff0000, v4
	v_lshlrev_b32_e32 v4, 16, v5
	v_and_b32_e32 v5, 0xffff0000, v5
	v_add_f32_e32 v2, 1.0, v2
	v_rcp_f32_e32 v8, v2
	v_mul_f32_e32 v2, 0xbfb8aa3b, v7
	v_exp_f32_e32 v2, v2
	s_nop 0
	v_add_f32_e32 v2, 1.0, v2
	v_rcp_f32_e32 v9, v2
	v_mul_f32_e32 v2, 0xbfb8aa3b, v4
	v_exp_f32_e32 v2, v2
	v_pk_mul_f32 v[6:7], v[8:9], v[6:7]
	s_nop 0
	v_pk_mul_f32 v[6:7], v[12:13], v[6:7]
	v_add_f32_e32 v2, 1.0, v2
	v_rcp_f32_e32 v8, v2
	v_mul_f32_e32 v2, 0xbfb8aa3b, v5
	v_exp_f32_e32 v2, v2
	v_cvt_pk_bf16_f32 v6, v6, v7
	v_add_f32_e32 v2, 1.0, v2
	v_rcp_f32_e32 v9, v2
	s_nop 0
	v_pk_mul_f32 v[4:5], v[8:9], v[4:5]
	s_nop 0
	v_pk_mul_f32 v[4:5], v[14:15], v[4:5]
	s_nop 0
	v_cvt_pk_bf16_f32 v7, v4, v5
	global_load_dwordx2 v[4:5], v[36:37], off offset:112
	s_nop 0
	global_store_dwordx2 v[0:1], v[6:7], off offset:96
	s_waitcnt vmcnt(1)
	v_lshlrev_b32_e32 v6, 16, v4
	v_mul_f32_e32 v2, 0xbfb8aa3b, v6
	v_exp_f32_e32 v2, v2
	v_and_b32_e32 v7, 0xffff0000, v4
	v_lshlrev_b32_e32 v4, 16, v5
	v_and_b32_e32 v5, 0xffff0000, v5
	v_add_f32_e32 v2, 1.0, v2
	v_rcp_f32_e32 v8, v2
	v_mul_f32_e32 v2, 0xbfb8aa3b, v7
	v_exp_f32_e32 v2, v2
	s_nop 0
	v_add_f32_e32 v2, 1.0, v2
	v_rcp_f32_e32 v9, v2
	v_mul_f32_e32 v2, 0xbfb8aa3b, v4
	v_exp_f32_e32 v2, v2
	v_pk_mul_f32 v[6:7], v[8:9], v[6:7]
	s_nop 0
	v_pk_mul_f32 v[8:9], v[16:17], v[6:7]
	v_add_f32_e32 v2, 1.0, v2
	v_rcp_f32_e32 v6, v2
	v_mul_f32_e32 v2, 0xbfb8aa3b, v5
	v_exp_f32_e32 v2, v2
	s_nop 0
	v_add_f32_e32 v2, 1.0, v2
	v_rcp_f32_e32 v7, v2
	v_cvt_pk_bf16_f32 v2, v8, v9
	v_lshl_add_u64 v[8:9], v[0:1], 0, s[6:7]
	global_store_dword v[0:1], v2, off offset:112
	v_pk_mul_f32 v[4:5], v[6:7], v[4:5]
	s_nop 0
	v_pk_mul_f32 v[6:7], v[18:19], v[4:5]

; __global__ void __launch_bounds__(256, 2) hybrid_megakernel(Params p, int ph_lo, int ph_hi, int do_sync) {
;     ...
;         while (true) {
;           if (tid == 0) s_item = atomicAdd(ctr, 1);
;           __syncthreads();
;           const int w = s_item;
;           __syncthreads();
;           if (w >= limit) break;
.LBB0_280:
	s_setprio 0
	s_mov_b64 s[6:7], 0
